# hand-written 2-at-a-time weight transposes; out-proj / ffn-out / next-layer low-rank weight tiles transposed by the non-latent WGs at the end of their scan-phase work
# speedup vs baseline: 1.0064x; 1.0064x over previous
.LBB0_4:
	v_readlane_b32 s11, v227, 0
	s_lshl_b32 s1, s11, 2
	s_lshl_b32 s20, s76, 2
	s_cmpk_lt_i32 s11, 0
	v_writelane_b32 v227, s1, 9
	s_cselect_b64 s[2:3], -1, 0
	v_writelane_b32 v227, s2, 10
	s_mul_hi_i32 s1, s11, 0x59493e15
	v_mov_b32_e32 v1, 0xb60
	v_writelane_b32 v227, s3, 11
	s_lshr_b32 s2, s1, 31
	s_ashr_i32 s1, s1, 10
	s_add_i32 s2, s1, s2
	s_mul_i32 s1, s2, 0xfffff488
	s_add_i32 s1, s1, s11
	s_cmpk_gt_i32 s1, 0x21f
	s_cselect_b64 s[6:7], -1, 0
	v_writelane_b32 v227, s6, 12
	s_cmpk_gt_u32 s1, 0x31f
	v_sub_co_u32_e32 v1, vcc, s1, v1
	v_writelane_b32 v227, s7, 13
	s_cselect_b64 s[6:7], -1, 0
	v_writelane_b32 v227, s6, 14
	s_cmpk_gt_u32 s1, 0x89f
	v_mov_b32_e32 v2, 0xb68
	v_writelane_b32 v227, s7, 15
	s_cselect_b64 s[6:7], -1, 0
	v_writelane_b32 v227, s6, 16
	s_mul_i32 s0, s77, s76
	s_movk_i32 s77, 0x3ff
	v_writelane_b32 v227, s7, 17
	s_xor_b64 s[6:7], vcc, -1
	v_writelane_b32 v227, s6, 18
	v_sub_co_u32_e32 v2, vcc, s1, v2
	s_nop 0
	v_writelane_b32 v227, s7, 19
	s_xor_b64 s[6:7], vcc, -1
	v_writelane_b32 v227, s6, 20
	s_cmpk_gt_u32 s1, 0xb6f
	s_mov_b32 s89, 0
	v_writelane_b32 v227, s7, 21
	s_cselect_b64 s[6:7], -1, 0
	v_writelane_b32 v227, s6, 22
	s_ashr_i32 s3, s2, 31
	s_lshl_b32 s5, s1, 5
	v_writelane_b32 v227, s7, 23
	s_lshl_b64 s[6:7], s[2:3], 17
	v_writelane_b32 v227, s6, 24
	s_add_i32 s5, s5, 0x7ffe9200
	s_and_b32 s5, s5, 0x7fffffc0
	v_writelane_b32 v227, s7, 25
	s_lshl_b64 s[6:7], s[2:3], 16
	v_writelane_b32 v227, s6, 26
	s_lshl_b32 s8, s2, 1
	s_mov_b64 s[70:71], 0x1000
	v_writelane_b32 v227, s7, 27
	v_writelane_b32 v227, s5, 28
	s_lshl_b32 s5, s11, 6
	s_and_b32 s6, s5, 64
	v_writelane_b32 v227, s6, 29
	v_readfirstlane_b32 s6, v2
	s_lshr_b32 s6, s6, 2
	s_add_i32 s6, s6, s8
	s_ashr_i32 s7, s6, 31
	s_lshl_b64 s[12:13], s[6:7], 16
	v_writelane_b32 v227, s12, 30
	s_lshl_b64 s[6:7], s[6:7], 15
	s_and_b32 s5, s5, 0xc0
	v_writelane_b32 v227, s13, 31
	v_writelane_b32 v227, s6, 32
	s_mov_b64 s[74:75], 0x1200
	v_mov_b32_e32 v154, 0x358637bd
	v_writelane_b32 v227, s7, 33
	v_writelane_b32 v227, s5, 34
	v_readfirstlane_b32 s5, v1
	s_lshr_b32 s5, s5, 2
	s_add_i32 s6, s5, s8
	s_ashr_i32 s7, s6, 31
	s_lshl_b64 s[8:9], s[6:7], 16
	v_writelane_b32 v227, s8, 35
	s_lshl_b64 s[6:7], s[6:7], 15
	s_mul_hi_i32 s5, s2, 0xb00000
	v_writelane_b32 v227, s9, 36
	v_writelane_b32 v227, s6, 37
	v_mov_b32_e32 v1, 0x100
	v_sub_co_u32_e32 v1, vcc, s11, v1
	v_writelane_b32 v227, s7, 38
	v_writelane_b32 v227, s5, 39
	s_mul_i32 s5, s2, 0xb00000
	v_writelane_b32 v227, s5, 40
	s_mul_hi_i32 s5, s2, 0x580000
	v_writelane_b32 v227, s5, 41
	s_mul_i32 s5, s2, 0x580000
	v_writelane_b32 v227, s5, 42
	s_add_i32 s5, s1, 0xf760
	s_and_b32 s6, s5, 0xffff
	s_mul_i32 s6, s6, 0xba2f
	s_lshr_b32 s6, s6, 21
	s_lshl_b32 s7, s6, 6
	s_mul_i32 s6, s6, 44
	s_sub_i32 s5, s5, s6
	s_lshl_b32 s5, s5, 6
	v_writelane_b32 v227, s7, 43
	s_and_b32 s5, s5, 0xffc0
	v_writelane_b32 v227, s5, 44
	s_mul_hi_i32 s5, s2, 0x1600000
	v_writelane_b32 v227, s5, 45
	s_mul_i32 s5, s2, 0x1600000
	v_writelane_b32 v227, s5, 46
	s_lshl_b32 s5, s1, 2
	s_add_i32 s6, s5, 0x7ffff380
	s_and_b32 s6, s6, 0x7fffffc0
	v_writelane_b32 v227, s6, 47
	s_lshl_b32 s6, s1, 6
	s_and_b32 s6, s6, 0x3c0
	v_writelane_b32 v227, s6, 48
	s_lshl_b64 s[6:7], s[2:3], 20
	v_writelane_b32 v227, s6, 49
	s_add_i32 s5, s5, 0x7ffff780
	s_and_b32 s3, s5, 0x7fffffc0
	v_writelane_b32 v227, s7, 50
	v_writelane_b32 v227, s3, 51
	s_mul_hi_i32 s3, s2, 0x880000
	v_writelane_b32 v227, s3, 52
	s_mul_i32 s3, s2, 0x880000
	v_writelane_b32 v227, s3, 53
	s_mul_hi_i32 s3, s2, 0x440000
	v_writelane_b32 v227, s3, 54
	s_mul_i32 s2, s2, 0x440000
	v_writelane_b32 v227, s2, 55
	s_ashr_i32 s2, s1, 31
	s_lshr_b32 s2, s2, 28
	s_add_i32 s2, s1, s2
	s_lshl_b32 s3, s2, 2
	s_and_b32 s2, s2, 0x3fffff0
	s_sub_i32 s1, s1, s2
	s_andn2_b32 s3, s3, 63
	s_lshl_b32 s1, s1, 6
	v_writelane_b32 v227, s3, 56
	s_cmpk_lt_i32 s11, 0x180
	v_writelane_b32 v227, s1, 57
	s_cselect_b64 s[2:3], -1, 0
	s_lshl_b32 s12, s11, 8
	s_lshl_b32 s13, s76, 8
	s_lshr_b32 s14, s11, 3
	v_writelane_b32 v227, s2, 58
	s_cmpk_lt_u32 s11, 0xb00
	s_mov_b32 s26, s13
	v_writelane_b32 v227, s3, 59
	s_cselect_b64 s[2:3], -1, 0
	s_lshl_b32 s1, s11, 3
	v_writelane_b32 v227, s2, 60
	s_and_b32 s30, s1, 56
	s_bfe_u32 s1, s11, 0x30003
	v_writelane_b32 v227, s3, 61
	s_or_b32 s1, s1, s30
	v_writelane_b32 v227, s1, 62
	s_lshr_b32 s1, s11, 6
	v_writelane_b32 v227, s1, 63
	s_lshr_b32 s1, s76, 3
	s_cmpk_lt_u32 s11, 0x200
	v_writelane_b32 v226, s1, 0
	s_cselect_b64 s[2:3], -1, 0
	v_writelane_b32 v226, s2, 1
	s_cmpk_gt_i32 s11, 0x7f
	s_mov_b32 s88, 0x800000
	v_writelane_b32 v226, s3, 2
	s_cselect_b64 s[2:3], -1, 0
	v_writelane_b32 v226, s2, 3
	s_add_i32 s15, s76, 0xffffff80
	s_add_i32 s1, s11, 0xffffff80
	s_and_b32 s5, s11, 0x7fffff80
	v_writelane_b32 v226, s3, 4
	s_and_b64 s[2:3], vcc, exec
	s_cselect_b32 s6, s11, s1
	s_cmpk_lg_i32 s5, 0x100
	s_cselect_b64 s[2:3], -1, 0
	s_cmpk_eq_i32 s5, 0x100
	v_readfirstlane_b32 s5, v1
	s_cselect_b32 s10, s5, s6
	s_cmpk_lg_i32 s76, 0x200
	s_cselect_b64 s[6:7], -1, 0
	s_and_b64 s[8:9], s[6:7], exec
	v_writelane_b32 v226, s15, 5
	s_cselect_b32 s31, s15, 0x180
	s_cselect_b32 s10, s1, s10
	s_mov_b64 s[2:3], -1
	v_writelane_b32 v226, s2, 6
	s_cmpk_lt_i32 s11, 0x100
	v_lshrrev_b32_e32 v1, 20, v0
	v_writelane_b32 v226, s3, 7
	s_cselect_b64 s[2:3], -1, 0
	s_or_b64 s[2:3], s[2:3], s[6:7]
	s_and_b64 s[2:3], s[2:3], exec
	s_cselect_b32 s15, s11, s1
	s_cmpk_lt_u32 s5, 0x80
	s_cselect_b32 s15, s5, s15
	s_cmpk_lt_i32 s15, 0x200
	s_cselect_b64 s[2:3], -1, 0
	s_lshr_b32 s1, s31, 31
	s_add_i32 s1, s31, s1
	s_ashr_i32 s1, s1, 1
	s_movk_i32 s1, 0x100
	s_add_i32 s6, s15, s1
	v_writelane_b32 v226, s2, 8
	s_cmpk_lt_i32 s15, 0x100
	v_lshrrev_b32_e32 v0, 10, v0
	v_writelane_b32 v226, s3, 9
	s_cselect_b64 s[2:3], -1, 0
	v_writelane_b32 v226, s2, 10
	s_cmpk_lt_i32 s15, 0x80
	v_or_b32_e32 v0, v0, v1
	v_writelane_b32 v226, s3, 11
	s_cselect_b64 s[2:3], -1, 0
	v_writelane_b32 v226, s2, 12
	s_bfe_i32 s1, s11, 0x10000
	s_and_b32 s7, s11, 1
	v_writelane_b32 v226, s3, 13
	s_ashr_i32 s2, s11, 5
	s_lshl_b32 s5, s2, 11
	s_and_b32 s3, s1, 0x7ff
	s_lshl_b32 s1, s11, 1
	v_writelane_b32 v226, s5, 14
	s_and_b32 s1, s1, 48
	s_bfe_u32 s8, s11, 0x20001
	s_or_b32 s5, s5, s3
	v_writelane_b32 v226, s1, 15
	s_lshl_b32 s1, s2, 2
	s_cmp_eq_u32 s7, 0
	s_cselect_b32 s16, 1, -1
	v_writelane_b32 v226, s1, 16
	s_mul_i32 s2, s16, 0x300
	v_writelane_b32 v226, s2, 17
	s_mul_i32 s2, s7, 0x900000
	s_mul_i32 s9, s8, 0xc0
	s_or_b32 s2, s2, s9
	v_writelane_b32 v226, s9, 18
	s_addk_i32 s2, 0xff40
	v_writelane_b32 v226, s2, 19
	s_add_i32 s42, s5, 0x1000
	s_mul_i32 s2, s7, 0xc00000
	v_writelane_b32 v226, s2, 20
	s_mul_i32 s5, s42, 0x300
	s_lshl_b32 s83, s16, 3
	v_writelane_b32 v226, s5, 21
	s_add_i32 s5, s83, s42
	s_mul_i32 s9, s5, 0x300
	s_add_i32 s5, s5, s83
	v_writelane_b32 v226, s9, 22
	s_mul_i32 s9, s5, 0x300
	s_add_i32 s5, s5, s83
	v_writelane_b32 v226, s9, 23
	s_mul_i32 s9, s5, 0x300
	s_add_i32 s5, s5, s83
	v_writelane_b32 v226, s9, 24
	s_mulk_i32 s5, 0x300
	s_lshl_b32 s2, s8, 6
	v_writelane_b32 v226, s5, 25
	s_add_i32 s5, s76, s11
	s_cmpk_lt_i32 s11, 0x300
	s_cselect_b64 s[18:19], -1, 0
	v_writelane_b32 v226, s18, 26
	s_cmpk_lt_u32 s11, 0x660
	v_and_or_b32 v0, v0, s77, v131
	v_writelane_b32 v226, s19, 27
	s_cselect_b64 s[18:19], -1, 0
	s_and_b32 s9, s11, 7
	v_writelane_b32 v226, s18, 28
	s_mul_i32 s17, s9, 12
	s_mul_i32 s9, s14, 0xab
	v_writelane_b32 v226, s19, 29
	s_bfe_u32 s9, s9, 0x5000b
	v_writelane_b32 v226, s9, 30
	s_mul_i32 s9, s9, 12
	s_sub_i32 s9, s14, s9
	s_and_b32 s9, s9, 0xff
	v_writelane_b32 v226, s14, 31
	s_add_i32 s9, s17, s9
	v_writelane_b32 v226, s17, 32
	s_cmp_lt_i32 s78, 0
	v_writelane_b32 v226, s9, 33
	s_cselect_b64 s[18:19], -1, 0
	v_writelane_b32 v226, s18, 34
	s_mov_b32 s1, -1
	s_movk_i32 s81, 0x6000
	v_writelane_b32 v226, s19, 35
	v_cmp_eq_u32_e64 s[18:19], 0, v0
	v_cvt_f32_u32_e32 v0, s13
	s_mov_b64 s[24:25], 0x80
	v_writelane_b32 v226, s18, 36
	s_mov_b64 s[36:37], 0x100
	v_rcp_iflag_f32_e32 v0, v0
	v_writelane_b32 v226, s19, 37
	v_readlane_b32 s18, v227, 7
	v_readlane_b32 s19, v227, 8
	s_load_dword s9, s[18:19], 0x230
	s_load_dwordx2 s[22:23], s[18:19], 0x1f8
	v_mul_f32_e32 v0, 0x4f7ffffe, v0
	v_cvt_u32_f32_e32 v0, v0
	s_mov_b64 s[62:63], 0x10080
	s_waitcnt lgkmcnt(0)
	s_mul_i32 s91, s0, s9
	s_add_u32 s40, s22, 0x200
	s_addc_u32 s41, s23, 0
	s_add_u32 s64, s22, 0x1000
	s_addc_u32 s65, s23, 0
	s_add_u32 s38, s22, 0x1100
	s_addc_u32 s39, s23, 0
	s_add_u32 s54, s22, 0x1200
	s_addc_u32 s55, s23, 0
	s_add_u32 s18, s22, 0x1300
	s_addc_u32 s19, s23, 0
	v_writelane_b32 v226, s18, 38
	s_cmp_eq_u32 s4, 15
	s_mov_b64 s[34:35], 0x20080
	v_writelane_b32 v226, s19, 39
	s_cselect_b64 s[18:19], -1, 0
	v_writelane_b32 v226, s18, 40
	s_cmp_eq_u32 s4, 14
	s_mov_b64 s[94:95], 0x30080
	v_writelane_b32 v226, s19, 41
	s_cselect_b64 s[18:19], -1, 0
	v_writelane_b32 v226, s18, 42
	s_cmp_eq_u32 s4, 13
	s_mov_b64 s[96:97], 0x20100
	v_writelane_b32 v226, s19, 43
	s_cselect_b64 s[18:19], -1, 0
	v_writelane_b32 v226, s18, 44
	s_cmp_eq_u32 s4, 12
	s_mov_b64 s[86:87], 0x30100
	v_writelane_b32 v226, s19, 45
	s_cselect_b64 s[18:19], -1, 0
	v_writelane_b32 v226, s18, 46
	s_cmp_eq_u32 s4, 11
	s_mov_b64 s[68:69], 0x40100
	v_writelane_b32 v226, s19, 47
	s_cselect_b64 s[18:19], -1, 0
	v_writelane_b32 v226, s18, 48
	s_cmp_eq_u32 s4, 10
	v_mov_b32_e32 v155, 0x3a27c5ac
	v_writelane_b32 v226, s19, 49
	s_cselect_b64 s[18:19], -1, 0
	v_writelane_b32 v226, s18, 50
	s_cmp_eq_u32 s4, 9
	s_movk_i32 s17, 0xc00
	v_writelane_b32 v226, s19, 51
	s_cselect_b64 s[18:19], -1, 0
	v_writelane_b32 v226, s18, 52
	s_cmp_eq_u32 s4, 8
	s_movk_i32 s82, 0xfefe
	v_writelane_b32 v226, s19, 53
	s_cselect_b64 s[18:19], -1, 0
	v_writelane_b32 v226, s18, 54
	s_cmp_eq_u32 s4, 7
	v_mov_b32_e32 v156, 0x3ca908c9
	v_writelane_b32 v226, s19, 55
	s_cselect_b64 s[18:19], -1, 0
	v_writelane_b32 v226, s18, 56
	s_cmp_eq_u32 s4, 6
	v_mov_b32_e32 v157, 0xbf1f24be
	v_writelane_b32 v226, s19, 57
	s_cselect_b64 s[18:19], -1, 0
	v_writelane_b32 v226, s18, 58
	s_cmp_eq_u32 s4, 5
	v_mov_b32_e32 v158, 0x3e642e9d
	v_writelane_b32 v226, s19, 59
	s_cselect_b64 s[18:19], -1, 0
	v_writelane_b32 v226, s18, 60
	s_cmp_eq_u32 s4, 4
	v_mov_b32_e32 v159, 0x3e91f4c4
	v_writelane_b32 v226, s19, 61
	s_cselect_b64 s[18:19], -1, 0
	v_writelane_b32 v226, s18, 62
	s_cmp_eq_u32 s4, 3
	v_mov_b32_e32 v160, 0x3c0881c4
	v_writelane_b32 v226, s19, 63
	s_cselect_b64 s[18:19], -1, 0
	v_writelane_b32 v225, s18, 0
	s_cmp_eq_u32 s4, 2
	v_mov_b32_e32 v161, 0xbab64f3b
	v_writelane_b32 v225, s19, 1
	s_cselect_b64 s[18:19], -1, 0
	v_writelane_b32 v225, s18, 2
	s_cmp_eq_u32 s4, 1
	s_mov_b32 s80, 0xfffff
	v_writelane_b32 v225, s19, 3
	s_cselect_b64 s[18:19], -1, 0
	v_writelane_b32 v225, s18, 4
	s_cmp_eq_u32 s4, 0
	s_mov_b32 s90, 0x300000
	v_writelane_b32 v225, s19, 5
	s_cselect_b64 s[18:19], -1, 0
	s_lshl_b32 s0, s4, 8
	s_add_u32 s0, s22, s0
	v_writelane_b32 v225, s18, 6
	s_addc_u32 s4, s23, 0
	v_mov_b32_e32 v162, 1
	v_writelane_b32 v225, s19, 7
	s_add_u32 s18, s0, 0x1400
	s_addc_u32 s19, s4, 0
	v_writelane_b32 v225, s18, 8
	v_mov_b32_e32 v163, 0x60
	v_mov_b32_e32 v164, 0x3b3504f3
	v_writelane_b32 v225, s19, 9
	s_add_u32 s18, s0, 0x2400
	s_addc_u32 s19, s4, 0
	v_writelane_b32 v225, s18, 10
	v_bfrev_b32_e32 v165, 60
	v_mov_b32_e32 v166, 0xf149f2ca
	v_writelane_b32 v225, s19, 11
	s_add_u32 s18, s22, 0x3400
	s_addc_u32 s19, s23, 0
	v_writelane_b32 v225, s18, 12
	v_mov_b32_e32 v167, 0x7fc
	v_bfrev_b32_e32 v168, 0.5
	v_writelane_b32 v225, s19, 13
	s_add_u32 s18, s22, 0x3500
	s_addc_u32 s19, s23, 0
	v_writelane_b32 v225, s18, 14
	s_cmpk_lt_u32 s10, 0x200
	s_mov_b64 s[22:23], 0x40080
	v_writelane_b32 v225, s19, 15
	v_writelane_b32 v225, s10, 16
	s_cselect_b64 s[18:19], -1, 0
	v_writelane_b32 v225, s18, 17
	s_lshl_b32 s0, s7, 16
	s_lshl_b32 s4, s8, 14
	v_writelane_b32 v225, s19, 18
	s_or_b32 s0, s0, s4
	v_writelane_b32 v225, s0, 19
	v_writelane_b32 v225, s12, 20
	s_add_i32 s0, s12, s13
	v_writelane_b32 v225, s0, 21
	s_lshl_b32 s0, s76, 10
	v_writelane_b32 v225, s0, 22
	v_writelane_b32 v225, s0, 23
	v_writelane_b32 v225, s0, 24
	v_writelane_b32 v225, s0, 25
	s_mov_b32 s12, s13
	s_mov_b32 s0, s89
	s_and_b64 s[0:1], s[12:13], s[0:1]
	v_writelane_b32 v225, s0, 26
	s_abs_i32 s4, s31
	s_lshl_b32 s33, s76, 9
	v_writelane_b32 v225, s1, 27
	s_sub_i32 s0, 0, s13
	v_mul_lo_u32 v1, s0, v0
	v_mul_hi_u32 v1, v0, v1
	v_add_u32_e32 v133, v0, v1
	v_cvt_f32_u32_e32 v0, s4
	v_writelane_b32 v225, s33, 28
	v_writelane_b32 v225, s33, 29
	s_mov_b32 s1, s13
	v_rcp_iflag_f32_e32 v0, v0
	v_writelane_b32 v225, s0, 30
	s_ashr_i32 s27, s13, 31
	v_mov_b32_e32 v1, 0
	v_mul_f32_e32 v0, 0x4f7ffffe, v0
	v_cvt_u32_f32_e32 v0, v0
	v_writelane_b32 v225, s1, 31
	s_ashr_i32 s0, s6, 31
	s_abs_i32 s1, s6
	s_sub_i32 s6, 0, s4
	v_readfirstlane_b32 s7, v0
	s_mul_i32 s6, s6, s7
	s_mul_hi_u32 s6, s7, s6
	s_add_i32 s7, s7, s6
	s_mul_hi_u32 s6, s1, s7
	s_mul_i32 s6, s6, s4
	v_cvt_f32_u32_e32 v0, s76
	s_sub_i32 s1, s1, s6
	s_sub_i32 s6, s1, s4
	s_cmp_ge_u32 s1, s4
	s_cselect_b32 s1, s6, s1
	v_rcp_iflag_f32_e32 v0, v0
	s_sub_i32 s6, s1, s4
	s_cmp_ge_u32 s1, s4
	s_cselect_b32 s1, s6, s1
	s_xor_b32 s1, s1, s0
	v_mul_f32_e32 v0, 0x4f7ffffe, v0
	s_sub_i32 s10, s1, s0
	v_cvt_u32_f32_e32 v0, v0
	s_cmpk_lt_i32 s10, 0x100
	s_cselect_b64 s[6:7], -1, 0
	v_writelane_b32 v225, s6, 32
	s_sub_i32 s4, 0, s76
	s_mov_b64 s[18:19], 0x50080
	v_writelane_b32 v225, s7, 33
	v_readfirstlane_b32 s6, v0
	s_mul_i32 s4, s4, s6
	s_mul_hi_u32 s4, s6, s4
	s_add_i32 s6, s6, s4
	s_mul_hi_u32 s4, s5, s6
	s_mul_i32 s4, s4, s76
	s_sub_i32 s4, s5, s4
	s_sub_i32 s7, s4, s76
	s_cmp_ge_u32 s4, s76
	s_cselect_b32 s4, s7, s4
	s_sub_i32 s7, s4, s76
	s_cmp_ge_u32 s4, s76
	s_cselect_b32 s4, s7, s4
	s_cmpk_lt_i32 s4, 0xc0
	v_writelane_b32 v225, s4, 34
	s_cselect_b64 s[8:9], -1, 0
	s_abs_i32 s4, s76
	v_cvt_f32_u32_e32 v0, s4
	v_writelane_b32 v225, s8, 35
	s_sub_i32 s7, 0, s4
	v_mov_b32_e32 v169, 0x7f800000
	v_rcp_iflag_f32_e32 v0, v0
	v_writelane_b32 v225, s9, 36
	v_mov_b32_e32 v170, 0x1000
	v_mov_b32_e32 v171, 0xfffff800
	v_mul_f32_e32 v0, 0x4f7ffffe, v0
	v_cvt_u32_f32_e32 v0, v0
	v_mov_b32_e32 v172, 0xffffff00
	v_mov_b32_e32 v173, 0x1800000
	v_mov_b32_e32 v174, 0xffc00000
	v_readfirstlane_b32 s8, v0
	s_mul_i32 s7, s7, s8
	s_mul_hi_u32 s7, s8, s7
	s_add_i32 s8, s8, s7
	s_mul_hi_u32 s7, s8, 0xc0
	s_mul_i32 s7, s7, s4
	s_sub_i32 s7, 0xc0, s7
	s_sub_i32 s9, s7, s4
	s_cmp_ge_u32 s7, s4
	s_cselect_b32 s7, s9, s7
	s_sub_i32 s9, s7, s4
	s_cmp_ge_u32 s7, s4
	s_cselect_b32 s7, s9, s7
	s_sub_i32 s7, s5, s7
	s_mul_hi_u32 s9, s7, s6
	s_mul_i32 s9, s9, s76
	s_sub_i32 s7, s7, s9
	s_sub_i32 s9, s7, s76
	s_cmp_ge_u32 s7, s76
	s_cselect_b32 s7, s9, s7
	s_sub_i32 s9, s7, s76
	s_cmp_ge_u32 s7, s76
	s_cselect_b32 s7, s9, s7
	v_writelane_b32 v225, s7, 37
	s_cmpk_lt_i32 s7, 0xc0
	s_mul_hi_u32 s7, s8, 0x180
	s_mul_i32 s7, s7, s4
	s_cselect_b64 s[12:13], -1, 0
	s_sub_i32 s7, 0x180, s7
	s_sub_i32 s9, s7, s4
	s_cmp_ge_u32 s7, s4
	s_cselect_b32 s7, s9, s7
	s_sub_i32 s9, s7, s4
	s_cmp_ge_u32 s7, s4
	s_cselect_b32 s7, s9, s7
	s_sub_i32 s7, s5, s7
	s_mul_hi_u32 s9, s7, s6
	s_mul_i32 s9, s9, s76
	s_sub_i32 s7, s7, s9
	s_sub_i32 s9, s7, s76
	s_cmp_ge_u32 s7, s76
	s_cselect_b32 s7, s9, s7
	s_sub_i32 s9, s7, s76
	v_writelane_b32 v225, s12, 38
	s_cmp_ge_u32 s7, s76
	s_cselect_b32 s7, s9, s7
	v_writelane_b32 v225, s13, 39
	v_writelane_b32 v225, s7, 40
	s_cmpk_lt_i32 s7, 0xc0
	s_mul_hi_u32 s7, s8, 0x240
	s_mul_i32 s7, s7, s4
	s_cselect_b64 s[12:13], -1, 0
	s_sub_i32 s7, 0x240, s7
	s_sub_i32 s9, s7, s4
	s_cmp_ge_u32 s7, s4
	s_cselect_b32 s7, s9, s7
	s_sub_i32 s9, s7, s4
	s_cmp_ge_u32 s7, s4
	s_cselect_b32 s7, s9, s7
	s_sub_i32 s7, s5, s7
	s_mul_hi_u32 s9, s7, s6
	s_mul_i32 s9, s9, s76
	s_sub_i32 s7, s7, s9
	s_sub_i32 s9, s7, s76
	s_cmp_ge_u32 s7, s76
	s_cselect_b32 s7, s9, s7
	s_sub_i32 s9, s7, s76
	v_writelane_b32 v225, s12, 41
	s_cmp_ge_u32 s7, s76
	s_cselect_b32 s7, s9, s7
	v_writelane_b32 v225, s13, 42
	v_writelane_b32 v225, s7, 43
	s_cmpk_lt_i32 s7, 0xc0
	s_mul_hi_u32 s7, s8, 0x300
	s_mul_i32 s7, s7, s4
	s_cselect_b64 s[12:13], -1, 0
	s_sub_i32 s7, 0x300, s7
	s_sub_i32 s8, s7, s4
	s_cmp_ge_u32 s7, s4
	s_cselect_b32 s7, s8, s7
	s_sub_i32 s8, s7, s4
	s_cmp_ge_u32 s7, s4
	s_cselect_b32 s4, s8, s7
	s_sub_i32 s4, s5, s4
	s_mul_hi_u32 s6, s4, s6
	s_mul_i32 s6, s6, s76
	s_sub_i32 s4, s4, s6
	s_sub_i32 s6, s4, s76
	s_cmp_ge_u32 s4, s76
	s_cselect_b32 s4, s6, s4
	s_sub_i32 s6, s4, s76
	s_cmp_ge_u32 s4, s76
	v_writelane_b32 v225, s12, 44
	s_cselect_b32 s4, s6, s4
	s_cmpk_lt_i32 s4, 0xc0
	v_writelane_b32 v225, s13, 45
	v_writelane_b32 v225, s4, 46
	s_cselect_b64 s[6:7], -1, 0
	v_writelane_b32 v225, s6, 47
	s_lshl_b32 s4, s5, 5
	s_add_i32 s4, s4, 0x7ffe9200
	v_writelane_b32 v225, s7, 48
	v_writelane_b32 v225, s4, 49
	s_lshl_b32 s4, s76, 5
	v_writelane_b32 v225, s4, 50
	s_lshl_b32 s4, s5, 2
	s_add_i32 s4, s4, 0x7ffff380
	v_writelane_b32 v225, s4, 51
	s_lshl_b32 s4, s5, 6
	v_writelane_b32 v225, s4, 52
	s_lshl_b32 s4, s76, 6
	v_writelane_b32 v225, s4, 53
	s_lshl_b64 s[4:5], s[26:27], 2
	v_writelane_b32 v225, s4, 54
	s_lshl_b64 s[28:29], s[26:27], 1
	v_mbcnt_lo_u32_b32 v0, -1, 0
	v_writelane_b32 v225, s5, 55
	s_lshl_b32 s4, s11, 18
	v_writelane_b32 v225, s4, 56
	s_lshl_b32 s4, s76, 20
	s_bitcmp1_b32 s15, 0
	v_writelane_b32 v225, s4, 57
	s_cselect_b64 s[4:5], -1, 0
	v_writelane_b32 v225, s4, 58
	s_bitcmp1_b32 s31, 0
	v_mbcnt_hi_u32_b32 v150, -1, v0
	v_writelane_b32 v225, s5, 59
	s_cselect_b64 s[4:5], -1, 0
	v_writelane_b32 v225, s4, 60
	s_bitcmp1_b32 s10, 0
	v_and_b32_e32 v0, 64, v150
	v_writelane_b32 v225, s5, 61
	v_writelane_b32 v225, s10, 62
	s_cselect_b64 s[4:5], -1, 0
	s_lshl_b32 s1, s1, 5
	s_lshl_b32 s0, s0, 5
	v_writelane_b32 v225, s4, 63
	s_sub_i32 s0, s1, s0
	s_ashr_i32 s21, s20, 31
	v_writelane_b32 v224, s5, 0
	v_writelane_b32 v224, 0, 40
	v_writelane_b32 v224, s0, 1
	s_lshl_b32 s0, s31, 5
	v_writelane_b32 v224, s0, 2
	v_writelane_b32 v224, s15, 3
	s_lshl_b32 s0, s15, 5
	v_writelane_b32 v224, s0, 4
	s_or_b32 s0, s3, 0x1000
	v_writelane_b32 v224, s0, 5
	v_writelane_b32 v224, s16, 6
	s_lshl_b32 s0, s16, 5
	v_writelane_b32 v224, s0, 7
	s_lshl_b32 s0, s11, 4
	v_writelane_b32 v224, s0, 8
	s_lshl_b32 s0, s76, 4
	v_writelane_b32 v224, s0, 9
	s_lshl_b64 s[0:1], s[20:21], 2
	v_writelane_b32 v224, s0, 10
	v_xor_b32_e32 v151, 16, v150
	v_add_u32_e32 v152, 64, v0
	v_writelane_b32 v224, s1, 11
	s_lshl_b64 s[0:1], s[20:21], 12
	v_writelane_b32 v224, s0, 12
	v_xor_b32_e32 v153, 32, v150
	s_mov_b64 s[10:11], 0x10100
	v_writelane_b32 v224, s1, 13
	s_mov_b32 s0, s20
	v_writelane_b32 v224, s0, 14
	s_mov_b32 s5, 0x100000
	v_mov_b32_e32 v175, 0x7fc00000
	v_writelane_b32 v224, s1, 15
	s_lshl_b64 s[0:1], s[20:21], 11
	v_writelane_b32 v224, s0, 16
	v_mov_b32_e32 v176, 0x461c4000
	v_mov_b32_e32 v177, 0x37000000
	v_writelane_b32 v224, s1, 17
	s_lshl_b32 s0, s2, 2
	v_writelane_b32 v224, s0, 18
	v_writelane_b32 v224, s30, 19
	v_writelane_b32 v224, s31, 20
	v_writelane_b32 v224, s42, 21
	v_writelane_b32 v224, s83, 22
	v_writelane_b32 v224, s91, 23
	v_writelane_b32 v224, s40, 24
	s_mov_b32 s0, 0x7f800000
	s_mov_b32 s1, 0x18000
	v_writelane_b32 v224, s41, 25
	v_writelane_b32 v224, s64, 26
	v_not_b32_e32 v178, 63
	v_not_b32_e32 v179, 31
	v_writelane_b32 v224, s65, 27
	v_writelane_b32 v224, s54, 28
	v_mov_b32_e32 v130, v1
	v_mov_b32_e32 v132, v1
	v_writelane_b32 v224, s55, 29
	v_writelane_b32 v224, s38, 30
	s_mov_b32 s31, s42
	s_nop 0
	v_writelane_b32 v224, s39, 31
	v_writelane_b32 v224, s28, 32
	s_nop 1
	v_writelane_b32 v224, s29, 33
	s_branch .LBB0_7

.LBB0_275:
	v_readlane_b32 s58, v224, 36
	v_readlane_b32 s59, v227, 0
	s_movk_i32 s60, 0x3d8
	s_mov_b32 s61, 0
	s_nop 0
	s_cmp_eq_u32 s58, 3
	s_cselect_b32 s60, 0x3c0, s60
	s_add_i32 s59, s59, 0xffffff80
	s_movk_i32 s38, 0x180
.Ltr_entry:
	s_waitcnt vmcnt(0) lgkmcnt(0)
	s_barrier
	v_readlane_b32 s100, v224, 34
	v_readlane_b32 s101, v224, 35
	v_and_b32_e32 v2, 63, v131
	v_lshrrev_b32_e32 v3, 6, v131
	v_and_b32_e32 v4, 31, v131
	v_bfe_u32 v5, v131, 5, 1
	v_mul_u32_u24_e32 v5, 0xb00, v5
	v_add_u32_e32 v4, v4, v5
	v_mul_u32_u24_e32 v6, 0x41, v2
	v_add_lshl_u32 v6, v6, v3, 2
	v_lshrrev_b32_e32 v7, 2, v131
	v_and_b32_e32 v8, 3, v131
	v_mul_u32_u24_e32 v9, 0x41, v7
	v_lshl_add_u32 v9, v8, 4, v9
	v_lshlrev_b32_e32 v9, 2, v9
	v_lshlrev_b32_e32 v8, 5, v8
.Ltr_loop:
	s_cmp_ge_u32 s59, s60
	s_cbranch_scc1 .Ltr_done
	s_cmp_eq_u32 s61, 0
	s_cbranch_scc0 .Ltr0_p
	s_add_i32 s2, s59, 0x7a0
	s_add_i32 s65, s59, 0x220
	s_cmpk_lt_u32 s59, 0x100
	s_cselect_b32 s2, s65, s2
	s_add_i32 s3, s58, 1
	s_cmpk_lt_u32 s59, 0x3c0
	s_cselect_b32 s3, s58, s3
	s_branch .Ltr0_a
.Ltr0_p:
	s_sub_i32 s2, s59, 0x1320
	s_mov_b32 s3, 0
	s_cmpk_gt_u32 s59, 0x1e7f
	s_cbranch_scc1 .Ltr0_a
	s_cmpk_ge_u32 s59, 0x7a0
	s_addc_u32 s3, s3, 0
	s_cmpk_ge_u32 s59, 0xf40
	s_addc_u32 s3, s3, 0
	s_cmpk_ge_u32 s59, 0x16e0
	s_addc_u32 s3, s3, 0
	s_mul_i32 s65, s3, 0x7a0
	s_sub_i32 s2, s59, s65
	s_add_i32 s65, s2, 0x100
	s_cmpk_lt_u32 s2, 0x220
	s_cselect_b32 s2, s2, s65
.Ltr0_a:
	s_mov_b64 s[72:73], 0
	s_cmpk_gt_u32 s2, 0x21f
	s_cbranch_scc1 .Ltr0_c1
	s_mov_b32 s20, s2
	s_movk_i32 s48, 0x58
	s_movk_i32 s56, 0x100
	s_movk_i32 s66, 0x880
	s_movk_i32 s67, 0x400
	s_lshr_b32 s21, s20, 4
	s_lshl_b32 s21, s21, 6
	s_and_b32 s64, s20, 15
	s_lshl_b32 s64, s64, 6
	s_mul_i32 s49, s3, 0x880000
	s_mul_i32 s57, s3, 0x440000
	s_branch .Ltr0_z
.Ltr0_c1:
	s_cmpk_gt_u32 s2, 0x31f
	s_cbranch_scc1 .Ltr0_c2
	s_sub_i32 s20, s2, 0x220
	s_movk_i32 s48, 0x60
	s_movk_i32 s56, 0x108
	s_movk_i32 s66, 0x400
	s_movk_i32 s67, 0x400
	s_lshr_b32 s21, s20, 4
	s_lshl_b32 s21, s21, 6
	s_and_b32 s64, s20, 15
	s_lshl_b32 s64, s64, 6
	s_lshl_b32 s49, s3, 22
	s_lshl_b32 s57, s3, 21
	s_branch .Ltr0_z
.Ltr0_c2:
	s_cmpk_gt_u32 s2, 0x89f
	s_cbranch_scc1 .Ltr0_c3
	s_sub_i32 s20, s2, 0x320
	s_movk_i32 s48, 0xc8
	s_movk_i32 s56, 0x110
	s_movk_i32 s66, 0x1600
	s_movk_i32 s67, 0x400
	s_lshr_b32 s21, s20, 4
	s_lshl_b32 s21, s21, 6
	s_and_b32 s64, s20, 15
	s_lshl_b32 s64, s64, 6
	s_mul_i32 s49, s3, 0x1600000
	s_mul_i32 s57, s3, 0xb00000
	s_mov_b64 s[72:73], -1
	s_branch .Ltr0_z
.Ltr0_c3:
	s_cmpk_gt_u32 s2, 0xb5f
	s_cbranch_scc1 .Ltr0_c4
	s_sub_i32 s20, s2, 0x8a0
	s_movk_i32 s48, 0xd0
	s_movk_i32 s56, 0x118
	s_movk_i32 s66, 0x400
	s_movk_i32 s67, 0xb00
	s_mul_i32 s21, s20, 0x5d2
	s_lshr_b32 s21, s21, 16
	s_mul_i32 s64, s21, 44
	s_sub_i32 s64, s20, s64
	s_lshl_b32 s64, s64, 6
	s_lshl_b32 s21, s21, 6
	s_mul_i32 s49, s3, 0xb00000
	s_mul_i32 s57, s3, 0x580000
	s_branch .Ltr0_z
.Ltr0_c4:
	s_cmpk_gt_u32 s2, 0xb67
	s_cbranch_scc1 .Ltr0_c5
	s_sub_i32 s20, s2, 0xb60
	s_movk_i32 s48, 0x80
	s_movk_i32 s56, 0x120
	s_movk_i32 s66, 0x100
	s_movk_i32 s67, 0x40
	s_lshr_b32 s64, s20, 2
	s_lshl_b32 s65, s3, 1
	s_add_i32 s65, s65, s64
	s_and_b32 s21, s20, 3
	s_lshl_b32 s21, s21, 6
	s_mov_b32 s64, 0
	s_lshl_b32 s49, s65, 16
	s_lshl_b32 s57, s65, 15
	s_branch .Ltr0_z
.Ltr0_c5:
	s_cmpk_gt_u32 s2, 0xb6f
	s_cbranch_scc1 .Ltr0_c6
	s_sub_i32 s20, s2, 0xb68
	s_movk_i32 s48, 0x90
	s_movk_i32 s56, 0x128
	s_movk_i32 s66, 0x100
	s_movk_i32 s67, 0x40
	s_lshr_b32 s64, s20, 2
	s_lshl_b32 s65, s3, 1
	s_add_i32 s65, s65, s64
	s_and_b32 s21, s20, 3
	s_lshl_b32 s21, s21, 6
	s_mov_b32 s64, 0
	s_lshl_b32 s49, s65, 16
	s_lshl_b32 s57, s65, 15
	s_branch .Ltr0_z
.Ltr0_c6:
	s_sub_i32 s20, s2, 0xb70
	s_movk_i32 s48, 0x98
	s_movk_i32 s56, 0x130
	s_movk_i32 s66, 0x100
	s_movk_i32 s67, 0x80
	s_lshr_b32 s21, s20, 1
	s_lshl_b32 s21, s21, 6
	s_and_b32 s64, s20, 1
	s_lshl_b32 s64, s64, 6
	s_lshl_b32 s49, s3, 17
	s_lshl_b32 s57, s3, 16
	s_branch .Ltr0_z
.Ltr0_z:
	s_lshr_b32 s65, s21, 7
	s_lshl_b32 s65, s65, 6
	s_bfe_u32 s20, s21, 0x10006
	s_lshl_b32 s20, s20, 5
	s_add_i32 s65, s65, s20
	s_cmp_lg_u64 s[72:73], 0
	s_cselect_b32 s65, s65, s21
	s_mul_i32 s20, s64, s66
	s_add_i32 s65, s65, s20
	s_lshl_b32 s65, s65, 2
	s_add_u32 s65, s65, s49
	s_mul_i32 s20, s21, s67
	s_add_i32 s20, s20, s64
	s_lshl_b32 s20, s20, 1
	s_add_u32 s20, s20, s57
	s_mov_b32 s21, s48
	s_mov_b32 s64, s56
	s_load_dwordx2 s[48:49], s[100:101], s21
	s_load_dwordx2 s[56:57], s[100:101], s64
	v_cndmask_b32_e64 v12, v2, v4, s[72:73]
	v_mul_lo_u32 v13, v3, s66
	v_add_lshl_u32 v10, v13, v12, 2
	v_mul_lo_u32 v13, v7, s67
	v_lshl_add_u32 v14, v13, 1, v8
	s_lshl_b32 s21, s66, 4
	s_waitcnt lgkmcnt(0)
	s_add_u32 s48, s48, s65
	s_addc_u32 s49, s49, 0
	s_add_u32 s56, s56, s20
	s_addc_u32 s57, s57, 0
	global_load_dword v20, v10, s[48:49]
	v_add_u32_e32 v10, s21, v10
	global_load_dword v21, v10, s[48:49]
	v_add_u32_e32 v10, s21, v10
	global_load_dword v22, v10, s[48:49]
	v_add_u32_e32 v10, s21, v10
	global_load_dword v23, v10, s[48:49]
	v_add_u32_e32 v10, s21, v10
	global_load_dword v24, v10, s[48:49]
	v_add_u32_e32 v10, s21, v10
	global_load_dword v25, v10, s[48:49]
	v_add_u32_e32 v10, s21, v10
	global_load_dword v26, v10, s[48:49]
	v_add_u32_e32 v10, s21, v10
	global_load_dword v27, v10, s[48:49]
	v_add_u32_e32 v10, s21, v10
	global_load_dword v28, v10, s[48:49]
	v_add_u32_e32 v10, s21, v10
	global_load_dword v29, v10, s[48:49]
	v_add_u32_e32 v10, s21, v10
	global_load_dword v30, v10, s[48:49]
	v_add_u32_e32 v10, s21, v10
	global_load_dword v31, v10, s[48:49]
	v_add_u32_e32 v10, s21, v10
	global_load_dword v32, v10, s[48:49]
	v_add_u32_e32 v10, s21, v10
	global_load_dword v33, v10, s[48:49]
	v_add_u32_e32 v10, s21, v10
	global_load_dword v34, v10, s[48:49]
	v_add_u32_e32 v10, s21, v10
	global_load_dword v35, v10, s[48:49]
	s_add_i32 s59, s59, s38
	s_cmp_ge_u32 s59, s60
	s_cselect_b32 s39, 0, 1
	s_cbranch_scc1 .Ltr_nosec
	s_cmp_eq_u32 s61, 0
	s_cbranch_scc0 .Ltr1_p
	s_add_i32 s2, s59, 0x7a0
	s_add_i32 s65, s59, 0x220
	s_cmpk_lt_u32 s59, 0x100
	s_cselect_b32 s2, s65, s2
	s_add_i32 s3, s58, 1
	s_cmpk_lt_u32 s59, 0x3c0
	s_cselect_b32 s3, s58, s3
	s_branch .Ltr1_a

.Ltr1_a:
	s_mov_b64 s[14:15], 0
	s_cmpk_gt_u32 s2, 0x21f
	s_cbranch_scc1 .Ltr1_c1
	s_mov_b32 s20, s2
	s_movk_i32 s84, 0x58
	s_movk_i32 s92, 0x100
	s_movk_i32 s52, 0x880
	s_movk_i32 s53, 0x400
	s_lshr_b32 s21, s20, 4
	s_lshl_b32 s21, s21, 6
	s_and_b32 s64, s20, 15
	s_lshl_b32 s64, s64, 6
	s_mul_i32 s85, s3, 0x880000
	s_mul_i32 s93, s3, 0x440000
	s_branch .Ltr1_z
.Ltr1_c1:
	s_cmpk_gt_u32 s2, 0x31f
	s_cbranch_scc1 .Ltr1_c2
	s_sub_i32 s20, s2, 0x220
	s_movk_i32 s84, 0x60
	s_movk_i32 s92, 0x108
	s_movk_i32 s52, 0x400
	s_movk_i32 s53, 0x400
	s_lshr_b32 s21, s20, 4
	s_lshl_b32 s21, s21, 6
	s_and_b32 s64, s20, 15
	s_lshl_b32 s64, s64, 6
	s_lshl_b32 s85, s3, 22
	s_lshl_b32 s93, s3, 21
	s_branch .Ltr1_z
.Ltr1_c2:
	s_cmpk_gt_u32 s2, 0x89f
	s_cbranch_scc1 .Ltr1_c3
	s_sub_i32 s20, s2, 0x320
	s_movk_i32 s84, 0xc8
	s_movk_i32 s92, 0x110
	s_movk_i32 s52, 0x1600
	s_movk_i32 s53, 0x400
	s_lshr_b32 s21, s20, 4
	s_lshl_b32 s21, s21, 6
	s_and_b32 s64, s20, 15
	s_lshl_b32 s64, s64, 6
	s_mul_i32 s85, s3, 0x1600000
	s_mul_i32 s93, s3, 0xb00000
	s_mov_b64 s[14:15], -1
	s_branch .Ltr1_z
.Ltr1_c3:
	s_cmpk_gt_u32 s2, 0xb5f
	s_cbranch_scc1 .Ltr1_c4
	s_sub_i32 s20, s2, 0x8a0
	s_movk_i32 s84, 0xd0
	s_movk_i32 s92, 0x118
	s_movk_i32 s52, 0x400
	s_movk_i32 s53, 0xb00
	s_mul_i32 s21, s20, 0x5d2
	s_lshr_b32 s21, s21, 16
	s_mul_i32 s64, s21, 44
	s_sub_i32 s64, s20, s64
	s_lshl_b32 s64, s64, 6
	s_lshl_b32 s21, s21, 6
	s_mul_i32 s85, s3, 0xb00000
	s_mul_i32 s93, s3, 0x580000
	s_branch .Ltr1_z
.Ltr1_c4:
	s_cmpk_gt_u32 s2, 0xb67
	s_cbranch_scc1 .Ltr1_c5
	s_sub_i32 s20, s2, 0xb60
	s_movk_i32 s84, 0x80
	s_movk_i32 s92, 0x120
	s_movk_i32 s52, 0x100
	s_movk_i32 s53, 0x40
	s_lshr_b32 s64, s20, 2
	s_lshl_b32 s65, s3, 1
	s_add_i32 s65, s65, s64
	s_and_b32 s21, s20, 3
	s_lshl_b32 s21, s21, 6
	s_mov_b32 s64, 0
	s_lshl_b32 s85, s65, 16
	s_lshl_b32 s93, s65, 15
	s_branch .Ltr1_z
.Ltr1_c5:
	s_cmpk_gt_u32 s2, 0xb6f
	s_cbranch_scc1 .Ltr1_c6
	s_sub_i32 s20, s2, 0xb68
	s_movk_i32 s84, 0x90
	s_movk_i32 s92, 0x128
	s_movk_i32 s52, 0x100
	s_movk_i32 s53, 0x40
	s_lshr_b32 s64, s20, 2
	s_lshl_b32 s65, s3, 1
	s_add_i32 s65, s65, s64
	s_and_b32 s21, s20, 3
	s_lshl_b32 s21, s21, 6
	s_mov_b32 s64, 0
	s_lshl_b32 s85, s65, 16
	s_lshl_b32 s93, s65, 15
	s_branch .Ltr1_z
.Ltr1_c6:
	s_sub_i32 s20, s2, 0xb70
	s_movk_i32 s84, 0x98
	s_movk_i32 s92, 0x130
	s_movk_i32 s52, 0x100
	s_movk_i32 s53, 0x80
	s_lshr_b32 s21, s20, 1
	s_lshl_b32 s21, s21, 6
	s_and_b32 s64, s20, 1
	s_lshl_b32 s64, s64, 6
	s_lshl_b32 s85, s3, 17
	s_lshl_b32 s93, s3, 16
	s_branch .Ltr1_z
.Ltr1_z:
	s_lshr_b32 s65, s21, 7
	s_lshl_b32 s65, s65, 6
	s_bfe_u32 s20, s21, 0x10006
	s_lshl_b32 s20, s20, 5
	s_add_i32 s65, s65, s20
	s_cmp_lg_u64 s[14:15], 0
	s_cselect_b32 s65, s65, s21
	s_mul_i32 s20, s64, s52
	s_add_i32 s65, s65, s20
	s_lshl_b32 s65, s65, 2
	s_add_u32 s65, s65, s85
	s_mul_i32 s20, s21, s53
	s_add_i32 s20, s20, s64
	s_lshl_b32 s20, s20, 1
	s_add_u32 s20, s20, s93
	s_mov_b32 s21, s84
	s_mov_b32 s64, s92
	s_load_dwordx2 s[84:85], s[100:101], s21
	s_load_dwordx2 s[92:93], s[100:101], s64
	v_cndmask_b32_e64 v12, v2, v4, s[14:15]
	v_mul_lo_u32 v13, v3, s52
	v_add_lshl_u32 v11, v13, v12, 2
	v_mul_lo_u32 v13, v7, s53
	v_lshl_add_u32 v15, v13, 1, v8
	s_lshl_b32 s21, s52, 4
	s_waitcnt lgkmcnt(0)
	s_add_u32 s84, s84, s65
	s_addc_u32 s85, s85, 0
	s_add_u32 s92, s92, s20
	s_addc_u32 s93, s93, 0
	global_load_dword v36, v11, s[84:85]
	v_add_u32_e32 v11, s21, v11
	global_load_dword v37, v11, s[84:85]
	v_add_u32_e32 v11, s21, v11
	global_load_dword v38, v11, s[84:85]
	v_add_u32_e32 v11, s21, v11
	global_load_dword v39, v11, s[84:85]
	v_add_u32_e32 v11, s21, v11
	global_load_dword v40, v11, s[84:85]
	v_add_u32_e32 v11, s21, v11
	global_load_dword v41, v11, s[84:85]
	v_add_u32_e32 v11, s21, v11
	global_load_dword v42, v11, s[84:85]
	v_add_u32_e32 v11, s21, v11
	global_load_dword v43, v11, s[84:85]
	v_add_u32_e32 v11, s21, v11
	global_load_dword v44, v11, s[84:85]
	v_add_u32_e32 v11, s21, v11
	global_load_dword v45, v11, s[84:85]
	v_add_u32_e32 v11, s21, v11
	global_load_dword v46, v11, s[84:85]
	v_add_u32_e32 v11, s21, v11
	global_load_dword v47, v11, s[84:85]
	v_add_u32_e32 v11, s21, v11
	global_load_dword v48, v11, s[84:85]
	v_add_u32_e32 v11, s21, v11
	global_load_dword v49, v11, s[84:85]
	v_add_u32_e32 v11, s21, v11
	global_load_dword v50, v11, s[84:85]
	v_add_u32_e32 v11, s21, v11
	global_load_dword v51, v11, s[84:85]
.Ltr_nosec:
	s_waitcnt vmcnt(0)
	ds_write_b32 v6, v20 offset:0
	ds_write_b32 v6, v21 offset:16
	ds_write_b32 v6, v22 offset:32
	ds_write_b32 v6, v23 offset:48
	ds_write_b32 v6, v24 offset:64
	ds_write_b32 v6, v25 offset:80
	ds_write_b32 v6, v26 offset:96
	ds_write_b32 v6, v27 offset:112
	ds_write_b32 v6, v28 offset:128
	ds_write_b32 v6, v29 offset:144
	ds_write_b32 v6, v30 offset:160
	ds_write_b32 v6, v31 offset:176
	ds_write_b32 v6, v32 offset:192
	ds_write_b32 v6, v33 offset:208
	ds_write_b32 v6, v34 offset:224
	ds_write_b32 v6, v35 offset:240
	s_cmp_eq_u32 s39, 0
	s_cbranch_scc1 .Ltr_w1
	ds_write_b32 v6, v36 offset:16640
	ds_write_b32 v6, v37 offset:16656
	ds_write_b32 v6, v38 offset:16672
	ds_write_b32 v6, v39 offset:16688
	ds_write_b32 v6, v40 offset:16704
	ds_write_b32 v6, v41 offset:16720
	ds_write_b32 v6, v42 offset:16736
	ds_write_b32 v6, v43 offset:16752
	ds_write_b32 v6, v44 offset:16768
	ds_write_b32 v6, v45 offset:16784
	ds_write_b32 v6, v46 offset:16800
	ds_write_b32 v6, v47 offset:16816
	ds_write_b32 v6, v48 offset:16832
	ds_write_b32 v6, v49 offset:16848
	ds_write_b32 v6, v50 offset:16864
	ds_write_b32 v6, v51 offset:16880
.Ltr_w1:
	s_waitcnt lgkmcnt(0)
	s_barrier
	ds_read_b32 v20, v9 offset:0
	ds_read_b32 v21, v9 offset:4
	ds_read_b32 v22, v9 offset:8
	ds_read_b32 v23, v9 offset:12
	ds_read_b32 v24, v9 offset:16
	ds_read_b32 v25, v9 offset:20
	ds_read_b32 v26, v9 offset:24
	ds_read_b32 v27, v9 offset:28
	ds_read_b32 v28, v9 offset:32
	ds_read_b32 v29, v9 offset:36
	ds_read_b32 v30, v9 offset:40
	ds_read_b32 v31, v9 offset:44
	ds_read_b32 v32, v9 offset:48
	ds_read_b32 v33, v9 offset:52
	ds_read_b32 v34, v9 offset:56
	ds_read_b32 v35, v9 offset:60
	s_waitcnt lgkmcnt(0)
	v_cvt_pk_f16_f32 v20, v20, v21
	v_cvt_pk_f16_f32 v21, v22, v23
	v_cvt_pk_f16_f32 v22, v24, v25
	v_cvt_pk_f16_f32 v23, v26, v27
	v_cvt_pk_f16_f32 v24, v28, v29
	v_cvt_pk_f16_f32 v25, v30, v31
	v_cvt_pk_f16_f32 v26, v32, v33
	v_cvt_pk_f16_f32 v27, v34, v35
	global_store_dwordx4 v14, v[20:23], s[56:57]
	global_store_dwordx4 v14, v[24:27], s[56:57] offset:16
	s_cmp_eq_u32 s39, 0
	s_cbranch_scc1 .Ltr_o1
	ds_read_b32 v36, v9 offset:16640
	ds_read_b32 v37, v9 offset:16644
	ds_read_b32 v38, v9 offset:16648
	ds_read_b32 v39, v9 offset:16652
	ds_read_b32 v40, v9 offset:16656
	ds_read_b32 v41, v9 offset:16660
	ds_read_b32 v42, v9 offset:16664
	ds_read_b32 v43, v9 offset:16668
	ds_read_b32 v44, v9 offset:16672
	ds_read_b32 v45, v9 offset:16676
	ds_read_b32 v46, v9 offset:16680
	ds_read_b32 v47, v9 offset:16684
	ds_read_b32 v48, v9 offset:16688
	ds_read_b32 v49, v9 offset:16692
	ds_read_b32 v50, v9 offset:16696
	ds_read_b32 v51, v9 offset:16700
	s_waitcnt lgkmcnt(0)
	v_cvt_pk_f16_f32 v36, v36, v37
	v_cvt_pk_f16_f32 v37, v38, v39
	v_cvt_pk_f16_f32 v38, v40, v41
	v_cvt_pk_f16_f32 v39, v42, v43
	v_cvt_pk_f16_f32 v40, v44, v45
	v_cvt_pk_f16_f32 v41, v46, v47
	v_cvt_pk_f16_f32 v42, v48, v49
	v_cvt_pk_f16_f32 v43, v50, v51
	global_store_dwordx4 v15, v[36:39], s[92:93]
	global_store_dwordx4 v15, v[40:43], s[92:93] offset:16
.Ltr_o1:
	s_barrier
	s_add_i32 s59, s59, s38
	s_branch .Ltr_loop
.Ltr_done:
	s_waitcnt vmcnt(0)
	s_cmp_eq_u32 s61, 0
	s_cbranch_scc1 .Ltr_ret_scan
	s_branch .Ltr_ret_prep

.LBB0_627:
	v_readlane_b32 s59, v227, 0
	s_mov_b32 s58, 0
	s_movk_i32 s60, 0x1e98
	s_mov_b32 s61, 1
	s_movk_i32 s38, 0x200
	s_branch .Ltr_entry
